# ln1: the four LN wave-sum butterflies per token pair done with DPP and permlane swaps instead of 24 ds_bpermute round trips
# speedup vs baseline: 1.0061x; 1.0015x over previous
.Lln1_nopf:
	s_lshl_b64 s[26:27], s[18:19], 10
	s_lshl_b64 s[28:29], s[16:17], 10
	v_lshlrev_b32_e32 v41, 16, v43
	v_lshlrev_b32_e32 v40, 16, v42
	v_and_b32_e32 v93, 0xffff0000, v43
	v_and_b32_e32 v92, 0xffff0000, v42
	v_lshlrev_b32_e32 v49, 16, v45
	v_lshlrev_b32_e32 v48, 16, v44
	v_and_b32_e32 v95, 0xffff0000, v45
	v_and_b32_e32 v94, 0xffff0000, v44
	v_lshlrev_b32_e32 v56, 16, v46
	v_and_b32_e32 v57, 0xffff0000, v46
	v_lshlrev_b32_e32 v58, 16, v47
	v_and_b32_e32 v59, 0xffff0000, v47
	v_pk_add_f32 v[42:43], v[40:41], v[92:93]
	v_lshlrev_b32_e32 v45, 16, v53
	v_lshlrev_b32_e32 v44, 16, v52
	v_and_b32_e32 v97, 0xffff0000, v53
	v_and_b32_e32 v96, 0xffff0000, v52
	v_pk_add_f32 v[46:47], v[48:49], v[94:95]
	v_lshlrev_b32_e32 v53, 16, v55
	v_lshlrev_b32_e32 v52, 16, v54
	v_and_b32_e32 v55, 0xffff0000, v55
	v_and_b32_e32 v54, 0xffff0000, v54
	v_lshlrev_b32_e32 v71, 16, v50
	v_and_b32_e32 v67, 0xffff0000, v50
	v_lshlrev_b32_e32 v69, 16, v51
	v_and_b32_e32 v65, 0xffff0000, v51
	v_add_f32_e32 v68, v56, v57
	v_add_f32_e32 v64, v58, v59
	v_add_f32_e32 v66, v42, v43
	v_pk_add_f32 v[42:43], v[44:45], v[96:97]
	v_pk_add_f32 v[50:51], v[52:53], v[54:55]
	v_pk_add_f32 v[46:47], v[46:47], v[46:47] op_sel:[0,1] op_sel_hi:[1,0]
	v_lshlrev_b32_e32 v60, 16, v62
	v_and_b32_e32 v61, 0xffff0000, v62
	v_lshlrev_b32_e32 v80, 16, v63
	v_and_b32_e32 v81, 0xffff0000, v63
	v_and_b32_e32 v75, 0xffff0000, v72
	v_pk_add_f32 v[62:63], v[68:69], v[64:65]
	v_add_f32_e32 v70, 0, v66
	v_add_f32_e32 v64, v42, v43
	v_mov_b32_e32 v47, v67
	v_pk_add_f32 v[42:43], v[50:51], v[50:51] op_sel:[0,1] op_sel_hi:[1,0]
	v_lshlrev_b32_e32 v79, 16, v72
	v_lshlrev_b32_e32 v77, 16, v73
	v_and_b32_e32 v73, 0xffff0000, v73
	v_add_f32_e32 v76, v60, v61
	v_add_f32_e32 v72, v80, v81
	v_add_f32_e32 v78, 0, v64
	v_pk_add_f32 v[46:47], v[70:71], v[46:47]
	v_mov_b32_e32 v43, v75
	v_pk_add_f32 v[50:51], v[76:77], v[72:73]
	v_pk_add_f32 v[46:47], v[46:47], v[62:63]
	v_pk_add_f32 v[42:43], v[78:79], v[42:43]
	v_add_f32_e32 v46, v46, v47
	v_pk_add_f32 v[42:43], v[42:43], v[50:51]
	v_add_f32_e32 v42, v42, v43
	s_waitcnt lgkmcnt(1)
	v_add_f32_dpp v46, v46, v46 quad_perm:[1,0,3,2] row_mask:0xf bank_mask:0xf
	s_waitcnt lgkmcnt(1)
	v_add_f32_dpp v42, v42, v42 quad_perm:[1,0,3,2] row_mask:0xf bank_mask:0xf
	s_waitcnt lgkmcnt(1)
	v_add_f32_dpp v46, v46, v46 quad_perm:[2,3,0,1] row_mask:0xf bank_mask:0xf
	s_waitcnt lgkmcnt(1)
	v_add_f32_dpp v42, v42, v42 quad_perm:[2,3,0,1] row_mask:0xf bank_mask:0xf
	s_waitcnt lgkmcnt(1)
	v_add_f32_dpp v46, v46, v46 row_half_mirror row_mask:0xf bank_mask:0xf
	s_waitcnt lgkmcnt(1)
	v_add_f32_dpp v42, v42, v42 row_half_mirror row_mask:0xf bank_mask:0xf
	s_waitcnt lgkmcnt(1)
	v_add_f32_dpp v46, v46, v46 row_mirror row_mask:0xf bank_mask:0xf
	s_waitcnt lgkmcnt(1)
	v_add_f32_dpp v42, v42, v42 row_mirror row_mask:0xf bank_mask:0xf
	s_waitcnt lgkmcnt(1)
	v_mov_b32_e32 v47, v46
	s_nop 1
	v_permlane16_swap_b32_e32 v47, v46
	v_add_f32_e32 v46, v46, v47
	s_waitcnt lgkmcnt(1)
	v_mov_b32_e32 v43, v42
	s_nop 1
	v_permlane16_swap_b32_e32 v43, v42
	v_add_f32_e32 v42, v42, v43
	s_waitcnt lgkmcnt(1)
	v_mov_b32_e32 v47, v46
	s_nop 1
	v_permlane32_swap_b32_e32 v47, v46
	v_add_f32_e32 v64, v46, v47
	v_fmac_f32_e32 v92, 0xba800000, v64
	s_waitcnt lgkmcnt(0)
	v_mov_b32_e32 v43, v42
	s_nop 1
	v_permlane32_swap_b32_e32 v43, v42
	v_add_f32_e32 v66, v42, v43
	v_fmac_f32_e32 v93, 0xba800000, v64
	v_fmac_f32_e32 v41, 0xba800000, v64
	v_fmac_f32_e32 v40, 0xba800000, v64
	v_fmac_f32_e32 v96, 0xba800000, v66
	v_fmac_f32_e32 v97, 0xba800000, v66
	v_fmac_f32_e32 v45, 0xba800000, v66
	v_mov_b32_e32 v42, v41
	v_mov_b32_e32 v43, v93
	v_mov_b32_e32 v41, v92
	v_fmac_f32_e32 v44, 0xba800000, v66
	v_pk_mul_f32 v[62:63], v[42:43], v[42:43]
	v_pk_mul_f32 v[92:93], v[40:41], v[40:41]
	v_mov_b32_e32 v46, v45
	v_mov_b32_e32 v47, v97
	v_mov_b32_e32 v45, v96
	v_fmac_f32_e32 v94, 0xba800000, v64
	v_fmac_f32_e32 v95, 0xba800000, v64
	v_fmac_f32_e32 v49, 0xba800000, v64
	v_pk_mov_b32 v[98:99], v[92:93], v[62:63] op_sel:[1,0]
	v_mov_b32_e32 v93, v63
	v_pk_mul_f32 v[62:63], v[46:47], v[46:47]
	v_pk_mul_f32 v[100:101], v[44:45], v[44:45]
	v_fmac_f32_e32 v48, 0xba800000, v64
	v_mov_b32_e32 v50, v49
	v_mov_b32_e32 v51, v95
	v_mov_b32_e32 v49, v94
	v_pk_add_f32 v[92:93], v[92:93], v[98:99]
	v_pk_mov_b32 v[98:99], v[100:101], v[62:63] op_sel:[1,0]
	v_mov_b32_e32 v101, v63
	v_pk_mul_f32 v[94:95], v[50:51], v[50:51]
	v_pk_mul_f32 v[96:97], v[48:49], v[48:49]
	v_pk_add_f32 v[62:63], v[98:99], v[100:101]
	v_fmac_f32_e32 v57, 0xba800000, v64
	v_pk_add_f32 v[98:99], v[62:63], v[62:63] op_sel_hi:[0,1]
	v_pk_mov_b32 v[62:63], v[96:97], v[94:95] op_sel:[1,0]
	v_mov_b32_e32 v97, v95
	v_fmac_f32_e32 v56, 0xba800000, v64
	v_fmac_f32_e32 v59, 0xba800000, v64
	v_fmac_f32_e32 v58, 0xba800000, v64
	v_fmac_f32_e32 v65, 0xba800000, v64
	v_fmac_f32_e32 v69, 0xba800000, v64
	v_fmac_f32_e32 v67, 0xba800000, v64
	v_fmac_f32_e32 v71, 0xba800000, v64
	v_mul_f32_e32 v64, v57, v57
	v_pk_add_f32 v[94:95], v[96:97], v[62:63]
	v_pk_fma_f32 v[100:101], v[56:57], v[56:57], v[64:65] op_sel_hi:[1,1,0]
	v_mul_f32_e32 v64, v59, v59
	v_mul_f32_e32 v68, v71, v71
	v_mul_f32_e32 v70, v67, v67
	v_mul_f32_e32 v72, v69, v69
	v_mul_f32_e32 v74, v65, v65
	v_pk_fma_f32 v[102:103], v[58:59], v[58:59], v[64:65] op_sel_hi:[1,1,0]
	v_pk_add_f32 v[92:93], v[92:93], v[92:93] op_sel:[0,1] op_sel_hi:[1,0]
	v_pk_add_f32 v[94:95], v[94:95], v[94:95] op_sel:[0,1] op_sel_hi:[1,0]
	v_mov_b32_e32 v101, v68
	v_mov_b32_e32 v103, v70
	v_mov_b32_e32 v93, v74
	v_mov_b32_e32 v95, v72
	v_pk_add_f32 v[100:101], v[100:101], v[102:103]
	v_pk_add_f32 v[92:93], v[92:93], v[94:95]
	v_fmac_f32_e32 v54, 0xba800000, v66
	v_pk_add_f32 v[92:93], v[100:101], v[92:93]
	v_fmac_f32_e32 v55, 0xba800000, v66
	v_fmac_f32_e32 v53, 0xba800000, v66
	v_add_f32_e32 v64, v92, v93
	v_fmac_f32_e32 v52, 0xba800000, v66
	v_mov_b32_e32 v62, v53
	v_mov_b32_e32 v63, v55
	v_mov_b32_e32 v53, v54
	v_pk_mul_f32 v[96:97], v[62:63], v[62:63]
	v_pk_mul_f32 v[54:55], v[52:53], v[52:53]
	v_fmac_f32_e32 v60, 0xba800000, v66
	v_pk_mov_b32 v[92:93], v[54:55], v[96:97] op_sel:[1,0]
	v_mov_b32_e32 v55, v97
	v_pk_add_f32 v[54:55], v[92:93], v[54:55]
	v_fmac_f32_e32 v61, 0xba800000, v66
	v_pk_add_f32 v[54:55], v[54:55], v[54:55] op_sel_hi:[0,1]
	s_waitcnt lgkmcnt(0)
	s_nop 0
	v_add_f32_dpp v54, v64, v64 quad_perm:[1,0,3,2] row_mask:0xf bank_mask:0xf
	v_fmac_f32_e32 v80, 0xba800000, v66
	v_fmac_f32_e32 v81, 0xba800000, v66
	v_fmac_f32_e32 v73, 0xba800000, v66
	v_fmac_f32_e32 v77, 0xba800000, v66
	s_waitcnt lgkmcnt(0)
	v_add_f32_dpp v64, v54, v54 quad_perm:[2,3,0,1] row_mask:0xf bank_mask:0xf
	v_mul_f32_e32 v54, v60, v60
	v_pk_fma_f32 v[92:93], v[60:61], v[60:61], v[54:55] op_sel_hi:[1,1,0]
	v_mul_f32_e32 v54, v80, v80
	v_pk_fma_f32 v[94:95], v[80:81], v[80:81], v[54:55] op_sel_hi:[1,1,0]
	s_waitcnt lgkmcnt(0)
	v_add_f32_dpp v54, v64, v64 row_half_mirror row_mask:0xf bank_mask:0xf
	v_fmac_f32_e32 v75, 0xba800000, v66
	v_fmac_f32_e32 v79, 0xba800000, v66
	v_mul_f32_e32 v92, v79, v79
	v_mul_f32_e32 v94, v75, v75
	s_waitcnt lgkmcnt(0)
	v_add_f32_dpp v64, v54, v54 row_mirror row_mask:0xf bank_mask:0xf
	v_mul_f32_e32 v98, v77, v77
	v_mul_f32_e32 v54, v73, v73
	v_pk_add_f32 v[92:93], v[92:93], v[94:95]
	v_pk_add_f32 v[54:55], v[98:99], v[54:55]
	s_waitcnt lgkmcnt(0)
	v_mov_b32_e32 v66, v64
	s_nop 1
	v_permlane16_swap_b32_e32 v66, v64
	v_add_f32_e32 v64, v64, v66
	v_pk_add_f32 v[54:55], v[92:93], v[54:55]
	v_lshl_add_u64 v[96:97], v[38:39], 0, s[20:21]
	v_add_f32_e32 v54, v54, v55
	v_lshl_add_u64 v[98:99], v[38:39], 0, s[22:23]
	s_waitcnt lgkmcnt(0)
	v_mov_b32_e32 v66, v64
	s_nop 1
	v_permlane32_swap_b32_e32 v66, v64
	v_add_f32_e32 v55, v64, v66
	v_fmamk_f32 v55, v55, 0x3a800000, v89
	v_mul_f32_e32 v64, 0x4f800000, v55
	v_cmp_gt_f32_e32 vcc, s24, v55
	v_lshl_add_u64 v[92:93], v[32:33], 0, s[26:27]
	s_waitcnt lgkmcnt(0)
	v_add_f32_dpp v54, v54, v54 quad_perm:[1,0,3,2] row_mask:0xf bank_mask:0xf
	v_cndmask_b32_e32 v55, v55, v64, vcc
	v_sqrt_f32_e32 v64, v55
	v_lshl_add_u64 v[94:95], v[32:33], 0, s[28:29]
	s_waitcnt lgkmcnt(0)
	v_add_f32_dpp v54, v54, v54 quad_perm:[2,3,0,1] row_mask:0xf bank_mask:0xf
	v_add_u32_e32 v68, -1, v64
	v_fma_f32 v70, -v68, v64, v55
	v_cmp_ge_f32_e64 s[12:13], 0, v70
	v_add_u32_e32 v70, 1, v64
	s_waitcnt lgkmcnt(0)
	v_add_f32_dpp v54, v54, v54 row_half_mirror row_mask:0xf bank_mask:0xf
	v_cndmask_b32_e64 v68, v64, v68, s[12:13]
	v_fma_f32 v64, -v70, v64, v55
	v_cmp_lt_f32_e64 s[12:13], 0, v64
	s_waitcnt lgkmcnt(0)
	v_add_f32_dpp v54, v54, v54 row_mirror row_mask:0xf bank_mask:0xf
	v_cndmask_b32_e64 v64, v68, v70, s[12:13]
	v_mul_f32_e32 v68, 0x37800000, v64
	v_cndmask_b32_e32 v64, v64, v68, vcc
	v_cmp_class_f32_e32 vcc, v55, v90
	s_waitcnt lgkmcnt(0)
	v_mov_b32_e32 v66, v54
	s_nop 1
	v_permlane16_swap_b32_e32 v66, v54
	v_add_f32_e32 v54, v54, v66
	v_cndmask_b32_e32 v55, v64, v55, vcc
	v_div_scale_f32 v64, s[12:13], v55, v55, 1.0
	v_rcp_f32_e32 v68, v64
	s_waitcnt lgkmcnt(0)
	v_mov_b32_e32 v66, v54
	s_nop 1
	v_permlane32_swap_b32_e32 v66, v54
	v_add_f32_e32 v54, v54, v66
	v_fmamk_f32 v54, v54, 0x3a800000, v89
	v_mul_f32_e32 v66, 0x4f800000, v54
	v_cmp_gt_f32_e64 s[12:13], s24, v54
	v_fma_f32 v70, -v64, v68, 1.0
	v_fmac_f32_e32 v68, v70, v68
	v_cndmask_b32_e64 v54, v54, v66, s[12:13]
	v_div_scale_f32 v70, vcc, 1.0, v55, 1.0
	v_sqrt_f32_e32 v66, v54
	v_mul_f32_e32 v72, v70, v68
	v_fma_f32 v74, -v64, v72, v70
	v_fmac_f32_e32 v72, v74, v68
	v_fma_f32 v64, -v64, v72, v70
	v_add_u32_e32 v70, -1, v66
	v_fma_f32 v74, -v70, v66, v54
	v_cmp_ge_f32_e64 s[14:15], 0, v74
	v_add_u32_e32 v74, 1, v66
	v_div_fmas_f32 v64, v64, v68, v72
	v_cndmask_b32_e64 v70, v66, v70, s[14:15]
	v_fma_f32 v66, -v74, v66, v54
	v_cmp_lt_f32_e64 s[14:15], 0, v66
	v_div_fixup_f32 v68, v64, v55, 1.0
	v_pk_mul_f32 v[40:41], v[40:41], v[68:69] op_sel_hi:[1,0]
	v_cndmask_b32_e64 v66, v70, v74, s[14:15]
	v_mul_f32_e32 v70, 0x37800000, v66
	v_cndmask_b32_e64 v66, v66, v70, s[12:13]
	v_cmp_class_f32_e64 s[12:13], v54, v90
	v_pk_fma_f32 v[40:41], v[0:1], v[40:41], v[8:9]
	v_pk_mul_f32 v[42:43], v[42:43], v[68:69] op_sel_hi:[1,0]
	v_cndmask_b32_e64 v54, v66, v54, s[12:13]
	v_div_scale_f32 v66, s[12:13], v54, v54, 1.0
	v_rcp_f32_e32 v70, v66
	v_pk_fma_f32 v[42:43], v[2:3], v[42:43], v[10:11]
	v_pk_mul_f32 v[48:49], v[48:49], v[68:69] op_sel_hi:[1,0]
	v_pk_mul_f32 v[56:57], v[68:69], v[56:57] op_sel_hi:[0,1]
	v_fma_f32 v55, -v66, v70, 1.0
	v_fmac_f32_e32 v70, v55, v70
	v_div_scale_f32 v55, vcc, 1.0, v54, 1.0
	v_mul_f32_e32 v64, v55, v70
	v_fma_f32 v72, -v66, v64, v55
	v_fmac_f32_e32 v64, v72, v70
	v_fma_f32 v55, -v66, v64, v55
	v_div_fmas_f32 v55, v55, v70, v64
	v_div_fixup_f32 v70, v55, v54, 1.0
	v_pk_mul_f32 v[44:45], v[44:45], v[70:71] op_sel_hi:[1,0]
	v_mov_b32_e32 v64, 0
	v_pk_mul_f32 v[54:55], v[46:47], v[70:71] op_sel_hi:[1,0]
	v_pk_fma_f32 v[46:47], v[0:1], v[44:45], v[8:9]
	v_cvt_pk_fp8_f32 v64, v40, v41
	v_mov_b32_e32 v66, 0
	v_cvt_pk_fp8_f32 v66, v46, v47
	v_pk_fma_f32 v[44:45], v[2:3], v[54:55], v[10:11]
	v_cvt_pk_fp8_f32 v64, v42, v43 op_sel:[0,0,1]
	v_cvt_pk_bf16_f32 v54, v40, v41
	v_cvt_pk_bf16_f32 v55, v42, v43
	v_cvt_pk_fp8_f32 v66, v44, v45 op_sel:[0,0,1]
	global_store_dwordx2 v[96:97], v[54:55], off
	v_cvt_pk_bf16_f32 v54, v46, v47
	v_cvt_pk_bf16_f32 v55, v44, v45
	global_store_dwordx2 v[98:99], v[54:55], off
	global_store_dword v[92:93], v64, off
	global_store_dword v[94:95], v66, off
	v_pk_mul_f32 v[54:55], v[50:51], v[68:69] op_sel_hi:[1,0]
	v_pk_fma_f32 v[50:51], v[4:5], v[48:49], v[12:13]
	v_pk_mul_f32 v[52:53], v[52:53], v[70:71] op_sel_hi:[1,0]
	v_mov_b32_e32 v64, 0
	v_pk_fma_f32 v[52:53], v[4:5], v[52:53], v[12:13]
	v_cvt_pk_fp8_f32 v64, v50, v51
	v_mov_b32_e32 v66, 0
	v_cvt_pk_fp8_f32 v66, v52, v53
	v_pk_fma_f32 v[54:55], v[6:7], v[54:55], v[14:15]
	v_pk_mul_f32 v[48:49], v[62:63], v[70:71] op_sel_hi:[1,0]
	v_cvt_pk_fp8_f32 v64, v54, v55 op_sel:[0,0,1]
	v_pk_fma_f32 v[48:49], v[6:7], v[48:49], v[14:15]
	v_cvt_pk_bf16_f32 v62, v50, v51
	v_cvt_pk_bf16_f32 v63, v54, v55
	v_cvt_pk_fp8_f32 v66, v48, v49 op_sel:[0,0,1]
	global_store_dwordx2 v[96:97], v[62:63], off offset:512
	v_cvt_pk_bf16_f32 v62, v52, v53
	v_cvt_pk_bf16_f32 v63, v48, v49
	global_store_dwordx2 v[98:99], v[62:63], off offset:512
	global_store_dword v[92:93], v64, off offset:256
	global_store_dword v[94:95], v66, off offset:256
	v_pk_fma_f32 v[62:63], v[16:17], v[56:57], v[24:25]
	v_pk_mul_f32 v[60:61], v[70:71], v[60:61] op_sel_hi:[0,1]
	v_mov_b32_e32 v64, 0
	v_pk_fma_f32 v[60:61], v[16:17], v[60:61], v[24:25]
	v_cvt_pk_fp8_f32 v64, v62, v63
	v_mov_b32_e32 v66, 0
	v_cvt_pk_fp8_f32 v66, v60, v61
	v_pk_mul_f32 v[58:59], v[68:69], v[58:59] op_sel_hi:[0,1]
	v_pk_fma_f32 v[58:59], v[18:19], v[58:59], v[26:27]
	v_pk_mul_f32 v[56:57], v[70:71], v[80:81] op_sel_hi:[0,1]
	v_pk_fma_f32 v[56:57], v[18:19], v[56:57], v[26:27]
	v_cvt_pk_fp8_f32 v64, v58, v59 op_sel:[0,0,1]
	v_cvt_pk_bf16_f32 v80, v62, v63
	v_cvt_pk_bf16_f32 v81, v58, v59
	v_cvt_pk_fp8_f32 v66, v56, v57 op_sel:[0,0,1]
	global_store_dwordx2 v[96:97], v[80:81], off offset:1024
	v_cvt_pk_bf16_f32 v80, v60, v61
	v_cvt_pk_bf16_f32 v81, v56, v57
	global_store_dwordx2 v[98:99], v[80:81], off offset:1024
	global_store_dword v[92:93], v64, off offset:512
	global_store_dword v[94:95], v66, off offset:512
	v_mov_b32_e32 v66, v71
	v_mov_b32_e32 v74, v79
	v_pk_mul_f32 v[66:67], v[68:69], v[66:67] op_sel_hi:[0,1]
	v_mov_b32_e32 v64, v69
	v_pk_mul_f32 v[74:75], v[70:71], v[74:75] op_sel_hi:[0,1]
	v_mov_b32_e32 v72, v77
	v_pk_mul_f32 v[64:65], v[68:69], v[64:65] op_sel_hi:[0,1]
	v_pk_fma_f32 v[68:69], v[20:21], v[66:67], v[28:29]
	v_pk_mul_f32 v[66:67], v[70:71], v[72:73] op_sel_hi:[0,1]
	v_pk_fma_f32 v[70:71], v[20:21], v[74:75], v[28:29]
	v_mov_b32_e32 v74, 0
	v_cvt_pk_fp8_f32 v74, v68, v69
	v_mov_b32_e32 v75, 0
	v_cvt_pk_fp8_f32 v75, v70, v71
	v_pk_fma_f32 v[64:65], v[22:23], v[64:65], v[30:31]
	v_pk_fma_f32 v[66:67], v[22:23], v[66:67], v[30:31]
	v_cvt_pk_fp8_f32 v74, v64, v65 op_sel:[0,0,1]
	v_cvt_pk_bf16_f32 v72, v68, v69
	v_cvt_pk_bf16_f32 v73, v64, v65
	v_cvt_pk_fp8_f32 v75, v66, v67 op_sel:[0,0,1]
	global_store_dwordx2 v[96:97], v[72:73], off offset:1536
	v_cvt_pk_bf16_f32 v72, v70, v71
	v_cvt_pk_bf16_f32 v73, v66, v67
	global_store_dwordx2 v[98:99], v[72:73], off offset:1536
	global_store_dword v[92:93], v74, off offset:768
	global_store_dword v[94:95], v75, off offset:768
	ds_read_b128 v[176:179], v88 offset:0
	ds_read_b128 v[180:183], v88 offset:1024
	ds_read_b128 v[184:187], v88 offset:2048
	ds_read_b128 v[188:191], v88 offset:3072
	ds_read_b128 v[192:195], v88 offset:4096
	ds_read_b128 v[196:199], v88 offset:5120
	ds_read_b128 v[200:203], v88 offset:6144
	ds_read_b128 v[204:207], v88 offset:7168
	s_waitcnt lgkmcnt(4)
	v_pk_mul_f32 v[208:209], v[40:41], v[176:177]
	v_pk_mul_f32 v[210:211], v[46:47], v[176:177]
	v_pk_fma_f32 v[208:209], v[42:43], v[178:179], v[208:209]
	v_pk_fma_f32 v[210:211], v[44:45], v[178:179], v[210:211]
	v_pk_fma_f32 v[208:209], v[50:51], v[180:181], v[208:209]
	v_pk_fma_f32 v[210:211], v[52:53], v[180:181], v[210:211]
	v_pk_fma_f32 v[208:209], v[54:55], v[182:183], v[208:209]
	v_pk_fma_f32 v[210:211], v[48:49], v[182:183], v[210:211]
	v_pk_fma_f32 v[208:209], v[62:63], v[184:185], v[208:209]
	v_pk_fma_f32 v[210:211], v[60:61], v[184:185], v[210:211]
	v_pk_fma_f32 v[208:209], v[58:59], v[186:187], v[208:209]
	v_pk_fma_f32 v[210:211], v[56:57], v[186:187], v[210:211]
	v_pk_fma_f32 v[208:209], v[68:69], v[188:189], v[208:209]
	v_pk_fma_f32 v[210:211], v[70:71], v[188:189], v[210:211]
	v_pk_fma_f32 v[208:209], v[64:65], v[190:191], v[208:209]
	v_pk_fma_f32 v[210:211], v[66:67], v[190:191], v[210:211]
	v_add_f32_e32 v142, v208, v209
	v_add_f32_e32 v143, v210, v211
	ds_read_b128 v[176:179], v88 offset:8192
	ds_read_b128 v[180:183], v88 offset:9216
	ds_read_b128 v[184:187], v88 offset:10240
	ds_read_b128 v[188:191], v88 offset:11264
	s_waitcnt lgkmcnt(4)
	v_pk_mul_f32 v[208:209], v[40:41], v[192:193]
	v_pk_mul_f32 v[210:211], v[46:47], v[192:193]
	v_pk_fma_f32 v[208:209], v[42:43], v[194:195], v[208:209]
	v_pk_fma_f32 v[210:211], v[44:45], v[194:195], v[210:211]
	v_pk_fma_f32 v[208:209], v[50:51], v[196:197], v[208:209]
	v_pk_fma_f32 v[210:211], v[52:53], v[196:197], v[210:211]
	v_pk_fma_f32 v[208:209], v[54:55], v[198:199], v[208:209]
	v_pk_fma_f32 v[210:211], v[48:49], v[198:199], v[210:211]
	v_pk_fma_f32 v[208:209], v[62:63], v[200:201], v[208:209]
	v_pk_fma_f32 v[210:211], v[60:61], v[200:201], v[210:211]
	v_pk_fma_f32 v[208:209], v[58:59], v[202:203], v[208:209]
	v_pk_fma_f32 v[210:211], v[56:57], v[202:203], v[210:211]
	v_pk_fma_f32 v[208:209], v[68:69], v[204:205], v[208:209]
	v_pk_fma_f32 v[210:211], v[70:71], v[204:205], v[210:211]
	v_pk_fma_f32 v[208:209], v[64:65], v[206:207], v[208:209]
	v_pk_fma_f32 v[210:211], v[66:67], v[206:207], v[210:211]
	v_add_f32_e32 v144, v208, v209
	v_add_f32_e32 v145, v210, v211
	ds_read_b128 v[192:195], v88 offset:12288
	ds_read_b128 v[196:199], v88 offset:13312
	ds_read_b128 v[200:203], v88 offset:14336
	ds_read_b128 v[204:207], v88 offset:15360
	s_waitcnt lgkmcnt(4)
	v_pk_mul_f32 v[208:209], v[40:41], v[176:177]
	v_pk_mul_f32 v[210:211], v[46:47], v[176:177]
	v_pk_fma_f32 v[208:209], v[42:43], v[178:179], v[208:209]
	v_pk_fma_f32 v[210:211], v[44:45], v[178:179], v[210:211]
	v_pk_fma_f32 v[208:209], v[50:51], v[180:181], v[208:209]
	v_pk_fma_f32 v[210:211], v[52:53], v[180:181], v[210:211]
	v_pk_fma_f32 v[208:209], v[54:55], v[182:183], v[208:209]
	v_pk_fma_f32 v[210:211], v[48:49], v[182:183], v[210:211]
	v_pk_fma_f32 v[208:209], v[62:63], v[184:185], v[208:209]
	v_pk_fma_f32 v[210:211], v[60:61], v[184:185], v[210:211]
	v_pk_fma_f32 v[208:209], v[58:59], v[186:187], v[208:209]
	v_pk_fma_f32 v[210:211], v[56:57], v[186:187], v[210:211]
	v_pk_fma_f32 v[208:209], v[68:69], v[188:189], v[208:209]
	v_pk_fma_f32 v[210:211], v[70:71], v[188:189], v[210:211]
	v_pk_fma_f32 v[208:209], v[64:65], v[190:191], v[208:209]
	v_pk_fma_f32 v[210:211], v[66:67], v[190:191], v[210:211]
	v_add_f32_e32 v146, v208, v209
	v_add_f32_e32 v147, v210, v211
	ds_read_b128 v[176:179], v88 offset:16384
	ds_read_b128 v[180:183], v88 offset:17408
	ds_read_b128 v[184:187], v88 offset:18432
	ds_read_b128 v[188:191], v88 offset:19456
	s_waitcnt lgkmcnt(4)
	v_pk_mul_f32 v[208:209], v[40:41], v[192:193]
	v_pk_mul_f32 v[210:211], v[46:47], v[192:193]
	v_pk_fma_f32 v[208:209], v[42:43], v[194:195], v[208:209]
	v_pk_fma_f32 v[210:211], v[44:45], v[194:195], v[210:211]
	v_pk_fma_f32 v[208:209], v[50:51], v[196:197], v[208:209]
	v_pk_fma_f32 v[210:211], v[52:53], v[196:197], v[210:211]
	v_pk_fma_f32 v[208:209], v[54:55], v[198:199], v[208:209]
	v_pk_fma_f32 v[210:211], v[48:49], v[198:199], v[210:211]
	v_pk_fma_f32 v[208:209], v[62:63], v[200:201], v[208:209]
	v_pk_fma_f32 v[210:211], v[60:61], v[200:201], v[210:211]
	v_pk_fma_f32 v[208:209], v[58:59], v[202:203], v[208:209]
	v_pk_fma_f32 v[210:211], v[56:57], v[202:203], v[210:211]
	v_pk_fma_f32 v[208:209], v[68:69], v[204:205], v[208:209]
	v_pk_fma_f32 v[210:211], v[70:71], v[204:205], v[210:211]
	v_pk_fma_f32 v[208:209], v[64:65], v[206:207], v[208:209]
	v_pk_fma_f32 v[210:211], v[66:67], v[206:207], v[210:211]
	v_add_f32_e32 v148, v208, v209
	v_add_f32_e32 v149, v210, v211
	ds_read_b128 v[192:195], v88 offset:20480
	ds_read_b128 v[196:199], v88 offset:21504
	ds_read_b128 v[200:203], v88 offset:22528
	ds_read_b128 v[204:207], v88 offset:23552
	s_waitcnt lgkmcnt(4)
	v_pk_mul_f32 v[208:209], v[40:41], v[176:177]
	v_pk_mul_f32 v[210:211], v[46:47], v[176:177]
	v_pk_fma_f32 v[208:209], v[42:43], v[178:179], v[208:209]
	v_pk_fma_f32 v[210:211], v[44:45], v[178:179], v[210:211]
	v_pk_fma_f32 v[208:209], v[50:51], v[180:181], v[208:209]
	v_pk_fma_f32 v[210:211], v[52:53], v[180:181], v[210:211]
	v_pk_fma_f32 v[208:209], v[54:55], v[182:183], v[208:209]
	v_pk_fma_f32 v[210:211], v[48:49], v[182:183], v[210:211]
	v_pk_fma_f32 v[208:209], v[62:63], v[184:185], v[208:209]
	v_pk_fma_f32 v[210:211], v[60:61], v[184:185], v[210:211]
	v_pk_fma_f32 v[208:209], v[58:59], v[186:187], v[208:209]
	v_pk_fma_f32 v[210:211], v[56:57], v[186:187], v[210:211]
	v_pk_fma_f32 v[208:209], v[68:69], v[188:189], v[208:209]
	v_pk_fma_f32 v[210:211], v[70:71], v[188:189], v[210:211]
	v_pk_fma_f32 v[208:209], v[64:65], v[190:191], v[208:209]
	v_pk_fma_f32 v[210:211], v[66:67], v[190:191], v[210:211]
	v_add_f32_e32 v150, v208, v209
	v_add_f32_e32 v151, v210, v211
	ds_read_b128 v[176:179], v88 offset:24576
	ds_read_b128 v[180:183], v88 offset:25600
	ds_read_b128 v[184:187], v88 offset:26624
	ds_read_b128 v[188:191], v88 offset:27648
	s_waitcnt lgkmcnt(4)
	v_pk_mul_f32 v[208:209], v[40:41], v[192:193]
	v_pk_mul_f32 v[210:211], v[46:47], v[192:193]
	v_pk_fma_f32 v[208:209], v[42:43], v[194:195], v[208:209]
	v_pk_fma_f32 v[210:211], v[44:45], v[194:195], v[210:211]
	v_pk_fma_f32 v[208:209], v[50:51], v[196:197], v[208:209]
	v_pk_fma_f32 v[210:211], v[52:53], v[196:197], v[210:211]
	v_pk_fma_f32 v[208:209], v[54:55], v[198:199], v[208:209]
	v_pk_fma_f32 v[210:211], v[48:49], v[198:199], v[210:211]
	v_pk_fma_f32 v[208:209], v[62:63], v[200:201], v[208:209]
	v_pk_fma_f32 v[210:211], v[60:61], v[200:201], v[210:211]
	v_pk_fma_f32 v[208:209], v[58:59], v[202:203], v[208:209]
	v_pk_fma_f32 v[210:211], v[56:57], v[202:203], v[210:211]
	v_pk_fma_f32 v[208:209], v[68:69], v[204:205], v[208:209]
	v_pk_fma_f32 v[210:211], v[70:71], v[204:205], v[210:211]
	v_pk_fma_f32 v[208:209], v[64:65], v[206:207], v[208:209]
	v_pk_fma_f32 v[210:211], v[66:67], v[206:207], v[210:211]
	v_add_f32_e32 v152, v208, v209
	v_add_f32_e32 v153, v210, v211
	ds_read_b128 v[192:195], v88 offset:28672
	ds_read_b128 v[196:199], v88 offset:29696
	ds_read_b128 v[200:203], v88 offset:30720
	ds_read_b128 v[204:207], v88 offset:31744
	s_waitcnt lgkmcnt(4)
	v_pk_mul_f32 v[208:209], v[40:41], v[176:177]
	v_pk_mul_f32 v[210:211], v[46:47], v[176:177]
	v_pk_fma_f32 v[208:209], v[42:43], v[178:179], v[208:209]
	v_pk_fma_f32 v[210:211], v[44:45], v[178:179], v[210:211]
	v_pk_fma_f32 v[208:209], v[50:51], v[180:181], v[208:209]
	v_pk_fma_f32 v[210:211], v[52:53], v[180:181], v[210:211]
	v_pk_fma_f32 v[208:209], v[54:55], v[182:183], v[208:209]
	v_pk_fma_f32 v[210:211], v[48:49], v[182:183], v[210:211]
	v_pk_fma_f32 v[208:209], v[62:63], v[184:185], v[208:209]
	v_pk_fma_f32 v[210:211], v[60:61], v[184:185], v[210:211]
	v_pk_fma_f32 v[208:209], v[58:59], v[186:187], v[208:209]
	v_pk_fma_f32 v[210:211], v[56:57], v[186:187], v[210:211]
	v_pk_fma_f32 v[208:209], v[68:69], v[188:189], v[208:209]
	v_pk_fma_f32 v[210:211], v[70:71], v[188:189], v[210:211]
	v_pk_fma_f32 v[208:209], v[64:65], v[190:191], v[208:209]
	v_pk_fma_f32 v[210:211], v[66:67], v[190:191], v[210:211]
	v_add_f32_e32 v154, v208, v209
	v_add_f32_e32 v155, v210, v211
	ds_read_b128 v[176:179], v88 offset:32768
	ds_read_b128 v[180:183], v88 offset:33792
	ds_read_b128 v[184:187], v88 offset:34816
	ds_read_b128 v[188:191], v88 offset:35840
	s_waitcnt lgkmcnt(4)
	v_pk_mul_f32 v[208:209], v[40:41], v[192:193]
	v_pk_mul_f32 v[210:211], v[46:47], v[192:193]
	v_pk_fma_f32 v[208:209], v[42:43], v[194:195], v[208:209]
	v_pk_fma_f32 v[210:211], v[44:45], v[194:195], v[210:211]
	v_pk_fma_f32 v[208:209], v[50:51], v[196:197], v[208:209]
	v_pk_fma_f32 v[210:211], v[52:53], v[196:197], v[210:211]
	v_pk_fma_f32 v[208:209], v[54:55], v[198:199], v[208:209]
	v_pk_fma_f32 v[210:211], v[48:49], v[198:199], v[210:211]
	v_pk_fma_f32 v[208:209], v[62:63], v[200:201], v[208:209]
	v_pk_fma_f32 v[210:211], v[60:61], v[200:201], v[210:211]
	v_pk_fma_f32 v[208:209], v[58:59], v[202:203], v[208:209]
	v_pk_fma_f32 v[210:211], v[56:57], v[202:203], v[210:211]
	v_pk_fma_f32 v[208:209], v[68:69], v[204:205], v[208:209]
	v_pk_fma_f32 v[210:211], v[70:71], v[204:205], v[210:211]
	v_pk_fma_f32 v[208:209], v[64:65], v[206:207], v[208:209]
	v_pk_fma_f32 v[210:211], v[66:67], v[206:207], v[210:211]
	v_add_f32_e32 v156, v208, v209
	v_add_f32_e32 v157, v210, v211
	ds_read_b128 v[192:195], v88 offset:36864
	ds_read_b128 v[196:199], v88 offset:37888
	ds_read_b128 v[200:203], v88 offset:38912
	ds_read_b128 v[204:207], v88 offset:39936
	s_waitcnt lgkmcnt(4)
	v_pk_mul_f32 v[208:209], v[40:41], v[176:177]
	v_pk_mul_f32 v[210:211], v[46:47], v[176:177]
	v_pk_fma_f32 v[208:209], v[42:43], v[178:179], v[208:209]
	v_pk_fma_f32 v[210:211], v[44:45], v[178:179], v[210:211]
	v_pk_fma_f32 v[208:209], v[50:51], v[180:181], v[208:209]
	v_pk_fma_f32 v[210:211], v[52:53], v[180:181], v[210:211]
	v_pk_fma_f32 v[208:209], v[54:55], v[182:183], v[208:209]
	v_pk_fma_f32 v[210:211], v[48:49], v[182:183], v[210:211]
	v_pk_fma_f32 v[208:209], v[62:63], v[184:185], v[208:209]
	v_pk_fma_f32 v[210:211], v[60:61], v[184:185], v[210:211]
	v_pk_fma_f32 v[208:209], v[58:59], v[186:187], v[208:209]
	v_pk_fma_f32 v[210:211], v[56:57], v[186:187], v[210:211]
	v_pk_fma_f32 v[208:209], v[68:69], v[188:189], v[208:209]
	v_pk_fma_f32 v[210:211], v[70:71], v[188:189], v[210:211]
	v_pk_fma_f32 v[208:209], v[64:65], v[190:191], v[208:209]
	v_pk_fma_f32 v[210:211], v[66:67], v[190:191], v[210:211]
	v_add_f32_e32 v158, v208, v209
	v_add_f32_e32 v159, v210, v211
	ds_read_b128 v[176:179], v88 offset:40960
	ds_read_b128 v[180:183], v88 offset:41984
	ds_read_b128 v[184:187], v88 offset:43008
	ds_read_b128 v[188:191], v88 offset:44032
	s_waitcnt lgkmcnt(4)
	v_pk_mul_f32 v[208:209], v[40:41], v[192:193]
	v_pk_mul_f32 v[210:211], v[46:47], v[192:193]
	v_pk_fma_f32 v[208:209], v[42:43], v[194:195], v[208:209]
	v_pk_fma_f32 v[210:211], v[44:45], v[194:195], v[210:211]
	v_pk_fma_f32 v[208:209], v[50:51], v[196:197], v[208:209]
	v_pk_fma_f32 v[210:211], v[52:53], v[196:197], v[210:211]
	v_pk_fma_f32 v[208:209], v[54:55], v[198:199], v[208:209]
	v_pk_fma_f32 v[210:211], v[48:49], v[198:199], v[210:211]
	v_pk_fma_f32 v[208:209], v[62:63], v[200:201], v[208:209]
	v_pk_fma_f32 v[210:211], v[60:61], v[200:201], v[210:211]
	v_pk_fma_f32 v[208:209], v[58:59], v[202:203], v[208:209]
	v_pk_fma_f32 v[210:211], v[56:57], v[202:203], v[210:211]
	v_pk_fma_f32 v[208:209], v[68:69], v[204:205], v[208:209]
	v_pk_fma_f32 v[210:211], v[70:71], v[204:205], v[210:211]
	v_pk_fma_f32 v[208:209], v[64:65], v[206:207], v[208:209]
	v_pk_fma_f32 v[210:211], v[66:67], v[206:207], v[210:211]
	v_add_f32_e32 v160, v208, v209
	v_add_f32_e32 v161, v210, v211
	ds_read_b128 v[192:195], v88 offset:45056
	ds_read_b128 v[196:199], v88 offset:46080
	ds_read_b128 v[200:203], v88 offset:47104
	ds_read_b128 v[204:207], v88 offset:48128
	s_waitcnt lgkmcnt(4)
	v_pk_mul_f32 v[208:209], v[40:41], v[176:177]
	v_pk_mul_f32 v[210:211], v[46:47], v[176:177]
	v_pk_fma_f32 v[208:209], v[42:43], v[178:179], v[208:209]
	v_pk_fma_f32 v[210:211], v[44:45], v[178:179], v[210:211]
	v_pk_fma_f32 v[208:209], v[50:51], v[180:181], v[208:209]
	v_pk_fma_f32 v[210:211], v[52:53], v[180:181], v[210:211]
	v_pk_fma_f32 v[208:209], v[54:55], v[182:183], v[208:209]
	v_pk_fma_f32 v[210:211], v[48:49], v[182:183], v[210:211]
	v_pk_fma_f32 v[208:209], v[62:63], v[184:185], v[208:209]
	v_pk_fma_f32 v[210:211], v[60:61], v[184:185], v[210:211]
	v_pk_fma_f32 v[208:209], v[58:59], v[186:187], v[208:209]
	v_pk_fma_f32 v[210:211], v[56:57], v[186:187], v[210:211]
	v_pk_fma_f32 v[208:209], v[68:69], v[188:189], v[208:209]
	v_pk_fma_f32 v[210:211], v[70:71], v[188:189], v[210:211]
	v_pk_fma_f32 v[208:209], v[64:65], v[190:191], v[208:209]
	v_pk_fma_f32 v[210:211], v[66:67], v[190:191], v[210:211]
	v_add_f32_e32 v162, v208, v209
	v_add_f32_e32 v163, v210, v211
	ds_read_b128 v[176:179], v88 offset:49152
	ds_read_b128 v[180:183], v88 offset:50176
	ds_read_b128 v[184:187], v88 offset:51200
	ds_read_b128 v[188:191], v88 offset:52224
	s_waitcnt lgkmcnt(4)
	v_pk_mul_f32 v[208:209], v[40:41], v[192:193]
	v_pk_mul_f32 v[210:211], v[46:47], v[192:193]
	v_pk_fma_f32 v[208:209], v[42:43], v[194:195], v[208:209]
	v_pk_fma_f32 v[210:211], v[44:45], v[194:195], v[210:211]
	v_pk_fma_f32 v[208:209], v[50:51], v[196:197], v[208:209]
	v_pk_fma_f32 v[210:211], v[52:53], v[196:197], v[210:211]
	v_pk_fma_f32 v[208:209], v[54:55], v[198:199], v[208:209]
	v_pk_fma_f32 v[210:211], v[48:49], v[198:199], v[210:211]
	v_pk_fma_f32 v[208:209], v[62:63], v[200:201], v[208:209]
	v_pk_fma_f32 v[210:211], v[60:61], v[200:201], v[210:211]
	v_pk_fma_f32 v[208:209], v[58:59], v[202:203], v[208:209]
	v_pk_fma_f32 v[210:211], v[56:57], v[202:203], v[210:211]
	v_pk_fma_f32 v[208:209], v[68:69], v[204:205], v[208:209]
	v_pk_fma_f32 v[210:211], v[70:71], v[204:205], v[210:211]
	v_pk_fma_f32 v[208:209], v[64:65], v[206:207], v[208:209]
	v_pk_fma_f32 v[210:211], v[66:67], v[206:207], v[210:211]
	v_add_f32_e32 v164, v208, v209
	v_add_f32_e32 v165, v210, v211
	ds_read_b128 v[192:195], v88 offset:53248
	ds_read_b128 v[196:199], v88 offset:54272
	ds_read_b128 v[200:203], v88 offset:55296
	ds_read_b128 v[204:207], v88 offset:56320
	s_waitcnt lgkmcnt(4)
	v_pk_mul_f32 v[208:209], v[40:41], v[176:177]
	v_pk_mul_f32 v[210:211], v[46:47], v[176:177]
	v_pk_fma_f32 v[208:209], v[42:43], v[178:179], v[208:209]
	v_pk_fma_f32 v[210:211], v[44:45], v[178:179], v[210:211]
	v_pk_fma_f32 v[208:209], v[50:51], v[180:181], v[208:209]
	v_pk_fma_f32 v[210:211], v[52:53], v[180:181], v[210:211]
	v_pk_fma_f32 v[208:209], v[54:55], v[182:183], v[208:209]
	v_pk_fma_f32 v[210:211], v[48:49], v[182:183], v[210:211]
	v_pk_fma_f32 v[208:209], v[62:63], v[184:185], v[208:209]
	v_pk_fma_f32 v[210:211], v[60:61], v[184:185], v[210:211]
	v_pk_fma_f32 v[208:209], v[58:59], v[186:187], v[208:209]
	v_pk_fma_f32 v[210:211], v[56:57], v[186:187], v[210:211]
	v_pk_fma_f32 v[208:209], v[68:69], v[188:189], v[208:209]
	v_pk_fma_f32 v[210:211], v[70:71], v[188:189], v[210:211]
	v_pk_fma_f32 v[208:209], v[64:65], v[190:191], v[208:209]
	v_pk_fma_f32 v[210:211], v[66:67], v[190:191], v[210:211]
	v_add_f32_e32 v166, v208, v209
	v_add_f32_e32 v167, v210, v211
	ds_read_b128 v[176:179], v88 offset:57344
	ds_read_b128 v[180:183], v88 offset:58368
	ds_read_b128 v[184:187], v88 offset:59392
	ds_read_b128 v[188:191], v88 offset:60416
	s_waitcnt lgkmcnt(4)
	v_pk_mul_f32 v[208:209], v[40:41], v[192:193]
	v_pk_mul_f32 v[210:211], v[46:47], v[192:193]
	v_pk_fma_f32 v[208:209], v[42:43], v[194:195], v[208:209]
	v_pk_fma_f32 v[210:211], v[44:45], v[194:195], v[210:211]
	v_pk_fma_f32 v[208:209], v[50:51], v[196:197], v[208:209]
	v_pk_fma_f32 v[210:211], v[52:53], v[196:197], v[210:211]
	v_pk_fma_f32 v[208:209], v[54:55], v[198:199], v[208:209]
	v_pk_fma_f32 v[210:211], v[48:49], v[198:199], v[210:211]
	v_pk_fma_f32 v[208:209], v[62:63], v[200:201], v[208:209]
	v_pk_fma_f32 v[210:211], v[60:61], v[200:201], v[210:211]
	v_pk_fma_f32 v[208:209], v[58:59], v[202:203], v[208:209]
	v_pk_fma_f32 v[210:211], v[56:57], v[202:203], v[210:211]
	v_pk_fma_f32 v[208:209], v[68:69], v[204:205], v[208:209]
	v_pk_fma_f32 v[210:211], v[70:71], v[204:205], v[210:211]
	v_pk_fma_f32 v[208:209], v[64:65], v[206:207], v[208:209]
	v_pk_fma_f32 v[210:211], v[66:67], v[206:207], v[210:211]
	v_add_f32_e32 v168, v208, v209
	v_add_f32_e32 v169, v210, v211
	ds_read_b128 v[192:195], v88 offset:61440
	ds_read_b128 v[196:199], v88 offset:62464
	ds_read_b128 v[200:203], v88 offset:63488
	ds_read_b128 v[204:207], v88 offset:64512
	s_waitcnt lgkmcnt(4)
	v_pk_mul_f32 v[208:209], v[40:41], v[176:177]
	v_pk_mul_f32 v[210:211], v[46:47], v[176:177]
	v_pk_fma_f32 v[208:209], v[42:43], v[178:179], v[208:209]
	v_pk_fma_f32 v[210:211], v[44:45], v[178:179], v[210:211]
	v_pk_fma_f32 v[208:209], v[50:51], v[180:181], v[208:209]
	v_pk_fma_f32 v[210:211], v[52:53], v[180:181], v[210:211]
	v_pk_fma_f32 v[208:209], v[54:55], v[182:183], v[208:209]
	v_pk_fma_f32 v[210:211], v[48:49], v[182:183], v[210:211]
	v_pk_fma_f32 v[208:209], v[62:63], v[184:185], v[208:209]
	v_pk_fma_f32 v[210:211], v[60:61], v[184:185], v[210:211]
	v_pk_fma_f32 v[208:209], v[58:59], v[186:187], v[208:209]
	v_pk_fma_f32 v[210:211], v[56:57], v[186:187], v[210:211]
	v_pk_fma_f32 v[208:209], v[68:69], v[188:189], v[208:209]
	v_pk_fma_f32 v[210:211], v[70:71], v[188:189], v[210:211]
	v_pk_fma_f32 v[208:209], v[64:65], v[190:191], v[208:209]
	v_pk_fma_f32 v[210:211], v[66:67], v[190:191], v[210:211]
	v_add_f32_e32 v170, v208, v209
	v_add_f32_e32 v171, v210, v211
	s_waitcnt lgkmcnt(0)
	v_pk_mul_f32 v[208:209], v[40:41], v[192:193]
	v_pk_mul_f32 v[210:211], v[46:47], v[192:193]
	v_pk_fma_f32 v[208:209], v[42:43], v[194:195], v[208:209]
	v_pk_fma_f32 v[210:211], v[44:45], v[194:195], v[210:211]
	v_pk_fma_f32 v[208:209], v[50:51], v[196:197], v[208:209]
	v_pk_fma_f32 v[210:211], v[52:53], v[196:197], v[210:211]
	v_pk_fma_f32 v[208:209], v[54:55], v[198:199], v[208:209]
	v_pk_fma_f32 v[210:211], v[48:49], v[198:199], v[210:211]
	v_pk_fma_f32 v[208:209], v[62:63], v[200:201], v[208:209]
	v_pk_fma_f32 v[210:211], v[60:61], v[200:201], v[210:211]
	v_pk_fma_f32 v[208:209], v[58:59], v[202:203], v[208:209]
	v_pk_fma_f32 v[210:211], v[56:57], v[202:203], v[210:211]
	v_pk_fma_f32 v[208:209], v[68:69], v[204:205], v[208:209]
	v_pk_fma_f32 v[210:211], v[70:71], v[204:205], v[210:211]
	v_pk_fma_f32 v[208:209], v[64:65], v[206:207], v[208:209]
	v_pk_fma_f32 v[210:211], v[66:67], v[206:207], v[210:211]
	v_add_f32_e32 v172, v208, v209
	v_add_f32_e32 v173, v210, v211
	v_cndmask_b32_e64 v43, v142, v158, s[0:1]
	ds_bpermute_b32 v43, v82, v43
	v_cndmask_b32_e64 v45, v144, v160, s[0:1]
	ds_bpermute_b32 v45, v82, v45
	v_cndmask_b32_e64 v46, v146, v162, s[0:1]
	ds_bpermute_b32 v46, v82, v46
	v_cndmask_b32_e64 v44, v158, v142, s[0:1]
	s_waitcnt lgkmcnt(2)
	v_add_f32_e32 v43, v44, v43
	v_cndmask_b32_e64 v44, v160, v144, s[0:1]
	s_waitcnt lgkmcnt(1)
	v_add_f32_e32 v44, v44, v45
	v_cndmask_b32_e64 v45, v162, v146, s[0:1]
	s_waitcnt lgkmcnt(0)
	v_add_f32_e32 v45, v45, v46
	v_cndmask_b32_e64 v46, v148, v164, s[0:1]
	ds_bpermute_b32 v46, v82, v46
	v_cndmask_b32_e64 v48, v150, v166, s[0:1]
	ds_bpermute_b32 v48, v82, v48
	v_cndmask_b32_e64 v49, v152, v168, s[0:1]
	ds_bpermute_b32 v49, v82, v49
	v_cndmask_b32_e64 v47, v164, v148, s[0:1]
	s_waitcnt lgkmcnt(2)
	v_add_f32_e32 v46, v47, v46
	v_cndmask_b32_e64 v47, v166, v150, s[0:1]
	s_waitcnt lgkmcnt(1)
	v_add_f32_e32 v47, v47, v48
	v_cndmask_b32_e64 v48, v168, v152, s[0:1]
	s_waitcnt lgkmcnt(0)
	v_add_f32_e32 v48, v48, v49
	v_cndmask_b32_e64 v49, v154, v170, s[0:1]
	ds_bpermute_b32 v49, v82, v49
	v_cndmask_b32_e64 v51, v156, v172, s[0:1]
	ds_bpermute_b32 v51, v82, v51
	v_cndmask_b32_e64 v50, v170, v154, s[0:1]
	v_cndmask_b32_e64 v41, v172, v156, s[0:1]
	s_waitcnt lgkmcnt(1)
	v_add_f32_e32 v49, v50, v49
	v_cndmask_b32_e64 v52, v43, v47, s[4:5]
	s_waitcnt lgkmcnt(0)
	v_add_f32_e32 v41, v41, v51
	v_cndmask_b32_e64 v43, v47, v43, s[4:5]
	v_cndmask_b32_e64 v47, v44, v48, s[4:5]
	v_cndmask_b32_e64 v44, v48, v44, s[4:5]
	v_cndmask_b32_e64 v48, v45, v49, s[4:5]
	ds_bpermute_b32 v52, v83, v52
	ds_bpermute_b32 v48, v83, v48
	v_cndmask_b32_e64 v50, v46, v41, s[4:5]
	ds_bpermute_b32 v47, v83, v47
	ds_bpermute_b32 v50, v83, v50
	v_cndmask_b32_e64 v45, v49, v45, s[4:5]
	s_waitcnt lgkmcnt(3)
	v_add_f32_e32 v43, v43, v52
	s_waitcnt lgkmcnt(2)
	v_add_f32_e32 v45, v45, v48
	v_cndmask_b32_e64 v41, v41, v46, s[4:5]
	s_waitcnt lgkmcnt(1)
	v_add_f32_e32 v44, v44, v47
	s_waitcnt lgkmcnt(0)
	v_add_f32_e32 v41, v41, v50
	v_cndmask_b32_e64 v46, v43, v45, s[6:7]
	ds_bpermute_b32 v46, v84, v46
	v_cndmask_b32_e64 v47, v44, v41, s[6:7]
	ds_bpermute_b32 v47, v84, v47
	v_cndmask_b32_e64 v42, v45, v43, s[6:7]
	v_cndmask_b32_e64 v41, v41, v44, s[6:7]
	v_cndmask_b32_e64 v44, v143, v159, s[0:1]
	s_waitcnt lgkmcnt(1)
	v_add_f32_e32 v42, v42, v46
	ds_bpermute_b32 v44, v82, v44
	v_cndmask_b32_e64 v46, v145, v161, s[0:1]
	s_waitcnt lgkmcnt(1)
	v_add_f32_e32 v41, v41, v47
	ds_bpermute_b32 v46, v82, v46
	v_cndmask_b32_e64 v47, v147, v163, s[0:1]
	ds_bpermute_b32 v47, v82, v47
	v_cndmask_b32_e64 v45, v159, v143, s[0:1]
	s_waitcnt lgkmcnt(2)
	v_add_f32_e32 v44, v45, v44
	v_cndmask_b32_e64 v45, v161, v145, s[0:1]
	s_waitcnt lgkmcnt(1)
	v_add_f32_e32 v45, v45, v46
	v_cndmask_b32_e64 v46, v163, v147, s[0:1]
	s_waitcnt lgkmcnt(0)
	v_add_f32_e32 v46, v46, v47
	v_cndmask_b32_e64 v47, v149, v165, s[0:1]
	ds_bpermute_b32 v47, v82, v47
	v_cndmask_b32_e64 v49, v151, v167, s[0:1]
	ds_bpermute_b32 v49, v82, v49
	v_cndmask_b32_e64 v50, v153, v169, s[0:1]
	ds_bpermute_b32 v50, v82, v50
	v_cndmask_b32_e64 v48, v165, v149, s[0:1]
	s_waitcnt lgkmcnt(2)
	v_add_f32_e32 v47, v48, v47
	v_cndmask_b32_e64 v48, v167, v151, s[0:1]
	s_waitcnt lgkmcnt(1)
	v_add_f32_e32 v48, v48, v49
	v_cndmask_b32_e64 v49, v169, v153, s[0:1]
	s_waitcnt lgkmcnt(0)
	v_add_f32_e32 v49, v49, v50
	v_cndmask_b32_e64 v50, v155, v171, s[0:1]
	v_cndmask_b32_e64 v52, v157, v173, s[0:1]
	ds_bpermute_b32 v50, v82, v50
	ds_bpermute_b32 v52, v82, v52
	v_cndmask_b32_e64 v51, v171, v155, s[0:1]
	v_cndmask_b32_e64 v40, v173, v157, s[0:1]
	v_cndmask_b32_e64 v53, v44, v48, s[4:5]
	s_waitcnt lgkmcnt(1)
	v_add_f32_e32 v50, v51, v50
	s_waitcnt lgkmcnt(0)
	v_add_f32_e32 v40, v40, v52
	v_cndmask_b32_e64 v44, v48, v44, s[4:5]
	v_cndmask_b32_e64 v48, v45, v49, s[4:5]
	v_cndmask_b32_e64 v45, v49, v45, s[4:5]
	v_cndmask_b32_e64 v49, v46, v50, s[4:5]
	v_cndmask_b32_e64 v51, v47, v40, s[4:5]
	ds_bpermute_b32 v53, v83, v53
	ds_bpermute_b32 v48, v83, v48
	ds_bpermute_b32 v49, v83, v49
	ds_bpermute_b32 v51, v83, v51
	v_cndmask_b32_e64 v46, v50, v46, s[4:5]
	v_cndmask_b32_e64 v40, v40, v47, s[4:5]
	s_waitcnt lgkmcnt(3)
	v_add_f32_e32 v44, v44, v53
	s_waitcnt lgkmcnt(2)
	v_add_f32_e32 v45, v45, v48
	s_waitcnt lgkmcnt(1)
	v_add_f32_e32 v46, v46, v49
	s_waitcnt lgkmcnt(0)
	v_add_f32_e32 v40, v40, v51
	v_cndmask_b32_e64 v47, v44, v46, s[6:7]
	v_cndmask_b32_e64 v48, v45, v40, s[6:7]
	ds_bpermute_b32 v47, v84, v47
	ds_bpermute_b32 v48, v84, v48
	v_cndmask_b32_e64 v44, v46, v44, s[6:7]
	v_cndmask_b32_e64 v40, v40, v45, s[6:7]
	v_cndmask_b32_e64 v43, v42, v41, s[8:9]
	s_waitcnt lgkmcnt(1)
	v_add_f32_e32 v44, v44, v47
	s_waitcnt lgkmcnt(0)
	v_add_f32_e32 v40, v40, v48
	ds_bpermute_b32 v43, v85, v43
	v_cndmask_b32_e64 v45, v44, v40, s[8:9]
	ds_bpermute_b32 v45, v85, v45
	v_cndmask_b32_e64 v41, v41, v42, s[8:9]
	v_cndmask_b32_e64 v40, v40, v44, s[8:9]
	s_waitcnt lgkmcnt(1)
	v_add_f32_e32 v41, v41, v43
	ds_bpermute_b32 v42, v86, v41
	s_waitcnt lgkmcnt(1)
	v_add_f32_e32 v40, v40, v45
	ds_bpermute_b32 v43, v86, v40
	s_waitcnt lgkmcnt(1)
	v_add_f32_e32 v41, v41, v42
	ds_bpermute_b32 v42, v87, v41
	s_waitcnt lgkmcnt(1)
	v_add_f32_e32 v40, v40, v43
	ds_bpermute_b32 v43, v87, v40
	s_waitcnt lgkmcnt(1)
	v_add_f32_e32 v41, v41, v42
	ds_bpermute_b32 v42, v82, v41
	s_waitcnt lgkmcnt(1)
	v_add_f32_e32 v40, v40, v43
	ds_bpermute_b32 v43, v82, v40
	s_waitcnt lgkmcnt(1)
	v_max_f32_e32 v42, v42, v42
	v_max_f32_e32 v42, v41, v42
	s_waitcnt lgkmcnt(0)
	v_max_f32_e32 v43, v43, v43
	ds_bpermute_b32 v44, v83, v42
	v_max_f32_e32 v43, v40, v43
	ds_bpermute_b32 v45, v83, v43
	s_waitcnt lgkmcnt(1)
	v_max_f32_e32 v44, v44, v44
	v_max_f32_e32 v42, v42, v44
	s_waitcnt lgkmcnt(0)
	v_max_f32_e32 v44, v45, v45
	v_max_f32_e32 v43, v43, v44
	ds_bpermute_b32 v45, v84, v42
	ds_bpermute_b32 v44, v84, v43
	s_waitcnt lgkmcnt(1)
	v_max_f32_e32 v45, v45, v45
	s_waitcnt lgkmcnt(0)
	v_max_f32_e32 v44, v44, v44
	v_max_f32_e32 v42, v42, v45
	v_max_f32_e32 v43, v43, v44
	ds_bpermute_b32 v45, v85, v42
	ds_bpermute_b32 v44, v85, v43
	s_waitcnt lgkmcnt(1)
	v_max_f32_e32 v45, v45, v45
	s_waitcnt lgkmcnt(0)
	v_max_f32_e32 v44, v44, v44
	v_max_f32_e32 v42, v42, v45
	v_max_f32_e32 v43, v43, v44
	v_sub_f32_e32 v41, v41, v42
	v_sub_f32_e32 v40, v40, v43
	v_mul_f32_e32 v41, 0x3fb8aa3b, v41
	v_mul_f32_e32 v40, 0x3fb8aa3b, v40
	v_exp_f32_e32 v41, v41
	v_exp_f32_e32 v40, v40
	ds_bpermute_b32 v42, v82, v41
	ds_bpermute_b32 v43, v82, v40
	s_waitcnt lgkmcnt(1)
	v_add_f32_e32 v42, v41, v42
	s_waitcnt lgkmcnt(0)
	v_add_f32_e32 v43, v40, v43
	ds_bpermute_b32 v44, v83, v42
	ds_bpermute_b32 v45, v83, v43
	s_waitcnt lgkmcnt(1)
	v_add_f32_e32 v42, v42, v44
	s_waitcnt lgkmcnt(0)
	v_add_f32_e32 v44, v43, v45
	ds_bpermute_b32 v43, v84, v42
	ds_bpermute_b32 v45, v84, v44
	s_waitcnt lgkmcnt(1)
	v_add_f32_e32 v43, v42, v43
	s_waitcnt lgkmcnt(0)
	v_add_f32_e32 v42, v44, v45
	ds_bpermute_b32 v45, v85, v43
	ds_bpermute_b32 v44, v85, v42
	s_and_saveexec_b64 s[12:13], s[10:11]
	s_cbranch_execz .LBB0_801
	s_waitcnt lgkmcnt(1)
	v_add_f32_e32 v43, v43, v45
	v_div_scale_f32 v45, s[14:15], v43, v43, v41
	v_rcp_f32_e32 v46, v45
	s_waitcnt lgkmcnt(0)
	v_add_f32_e32 v44, v42, v44
	v_fma_f32 v42, -v45, v46, 1.0
	v_fmac_f32_e32 v46, v42, v46
	v_div_scale_f32 v42, vcc, v41, v43, v41
	v_mul_f32_e32 v47, v42, v46
	v_fma_f32 v48, -v45, v47, v42
	v_fmac_f32_e32 v47, v48, v46
	v_fma_f32 v42, -v45, v47, v42
	v_div_scale_f32 v45, s[14:15], v44, v44, v40
	v_div_fmas_f32 v42, v42, v46, v47
	v_rcp_f32_e32 v46, v45
	v_div_fixup_f32 v41, v42, v43, v41
	v_lshl_add_u64 v[42:43], s[18:19], 2, v[34:35]
	global_store_dword v[42:43], v41, off
	v_fma_f32 v41, -v45, v46, 1.0
	v_fmac_f32_e32 v46, v41, v46
	v_div_scale_f32 v41, vcc, v40, v44, v40
	v_mul_f32_e32 v42, v41, v46
	v_fma_f32 v43, -v45, v42, v41
	v_fmac_f32_e32 v42, v43, v46
	v_fma_f32 v41, -v45, v42, v41
	v_div_fmas_f32 v41, v41, v46, v42
	v_div_fixup_f32 v42, v41, v44, v40
	v_lshl_add_u64 v[40:41], s[16:17], 2, v[34:35]
	global_store_dword v[40:41], v42, off
	s_branch .LBB0_801
